# strategy 7.12: FAST range checks of the first two phases made branch-free without EXEC save/restore (same predicate), on top of v39
# speedup vs baseline: 1.0084x; 1.0025x over previous
.LBB0_441:
	s_and_b32 s48, s33, 2
	s_add_i32 s4, s33, -1
	s_and_b32 s49, s4, 3
	s_mul_i32 s4, s48, 0x4800
	v_add_u32_e32 v168, s4, v184
	s_cmp_eq_u32 s33, 0
	ds_read_b128 v[164:167], v168 offset:96
	s_cselect_b64 s[6:7], -1, 0
	s_mulk_i32 s49, 0x4800
	s_and_b64 s[4:5], s[6:7], exec
	s_cselect_b32 s4, 0, s49
	v_add_u32_e32 v84, s4, v184
	v_exp_f32_e32 v64, v64
	v_exp_f32_e32 v65, v65
	s_nop 0
	v_add_f32_e32 v113, v65, v64
	v_cvt_pk_bf16_f32 v112, v64, v65
	ds_read_b128 v[186:189], v84 offset:9280
	ds_read_b128 v[190:193], v84 offset:9312
	ds_read_b128 v[194:197], v84 offset:13888
	ds_read_b128 v[198:201], v84 offset:13920
	v_mfma_f32_32x32x16_bf16 v[80:95], v[80:83], v[148:151], 0
	v_exp_f32_e32 v64, v66
	v_exp_f32_e32 v65, v67
	v_add_f32_e32 v66, v64, v113
	v_add_f32_e32 v66, v65, v66
	v_cvt_pk_bf16_f32 v113, v64, v65
	v_mfma_f32_32x32x16_bf16 v[80:95], v[108:111], v[152:155], v[80:95]
	v_exp_f32_e32 v64, v68
	v_exp_f32_e32 v65, v69
	v_add_f32_e32 v66, v64, v66
	v_cvt_pk_bf16_f32 v114, v64, v65
	v_add_f32_e32 v64, v65, v66
	v_mfma_f32_32x32x16_bf16 v[80:95], v[104:107], v[156:159], v[80:95]
	v_exp_f32_e32 v65, v70
	v_exp_f32_e32 v66, v71
	v_add_f32_e32 v64, v65, v64
	v_cvt_pk_bf16_f32 v115, v65, v66
	v_add_f32_e32 v64, v66, v64
	s_waitcnt lgkmcnt(4)
	v_mfma_f32_32x32x16_bf16 v[80:95], v[164:167], v[160:163], v[80:95]
	v_exp_f32_e32 v65, v72
	v_exp_f32_e32 v66, v73
	v_add_f32_e32 v64, v65, v64
	v_cvt_pk_bf16_f32 v104, v65, v66
	v_add_f32_e32 v64, v66, v64
	s_waitcnt lgkmcnt(0)
	v_mfma_f32_32x32x16_bf16 v[16:31], v[186:189], v[96:99], v[16:31]
	v_exp_f32_e32 v65, v74
	v_exp_f32_e32 v66, v75
	v_add_f32_e32 v64, v65, v64
	v_cvt_pk_bf16_f32 v105, v65, v66
	v_add_f32_e32 v64, v66, v64
	v_mfma_f32_32x32x16_bf16 v[16:31], v[190:193], v[100:103], v[16:31]
	v_exp_f32_e32 v65, v76
	v_exp_f32_e32 v66, v77
	v_add_f32_e32 v64, v65, v64
	v_cvt_pk_bf16_f32 v106, v65, v66
	v_add_f32_e32 v64, v66, v64
	v_mfma_f32_32x32x16_bf16 v[0:15], v[194:197], v[96:99], v[0:15]
	v_exp_f32_e32 v65, v78
	v_exp_f32_e32 v66, v79
	v_add_f32_e32 v64, v65, v64
	v_cvt_pk_bf16_f32 v107, v65, v66
	v_add_f32_e32 v185, v66, v64
	v_exp_f32_e32 v68, v80
	v_exp_f32_e32 v69, v81
	s_nop 0
	v_add_f32_e32 v80, v69, v68
	v_cvt_pk_bf16_f32 v96, v68, v69
	v_mfma_f32_32x32x16_bf16 v[0:15], v[198:201], v[100:103], v[0:15]
	ds_read_b128 v[64:67], v168 offset:4608
	ds_read_b128 v[164:167], v168 offset:4640
	ds_read_b128 v[108:111], v168 offset:4672
	v_cmp_nge_f32_e64 s[4:5], s62, v185
	v_cmp_gt_f32_e32 vcc, s75, v185
	s_and_b64 vcc, s[6:7], vcc
	s_or_b64 s[4:5], s[4:5], vcc
	ds_read_b128 v[186:189], v168 offset:4704
	s_waitcnt lgkmcnt(1)
	v_mfma_f32_32x32x16_bf16 v[64:79], v[64:67], v[116:119], 0
	ds_read_b128 v[190:193], v168 offset:9216
	ds_read_b128 v[194:197], v168 offset:9248
	ds_read_b128 v[198:201], v168 offset:13824
	ds_read_b128 v[230:233], v168 offset:13856
	v_exp_f32_e32 v81, v82
	v_exp_f32_e32 v82, v83
	v_add_f32_e32 v80, v81, v80
	v_add_f32_e32 v80, v82, v80
	v_cvt_pk_bf16_f32 v97, v81, v82
	v_mfma_f32_32x32x16_bf16 v[64:79], v[164:167], v[120:123], v[64:79]
	v_exp_f32_e32 v81, v84
	v_exp_f32_e32 v82, v85
	v_add_f32_e32 v80, v81, v80
	v_cvt_pk_bf16_f32 v98, v81, v82
	v_add_f32_e32 v80, v82, v80
	v_mfma_f32_32x32x16_bf16 v[64:79], v[108:111], v[124:127], v[64:79]
	v_exp_f32_e32 v81, v86
	v_exp_f32_e32 v82, v87
	v_add_f32_e32 v80, v81, v80
	v_cvt_pk_bf16_f32 v99, v81, v82
	v_add_f32_e32 v80, v82, v80
	s_waitcnt lgkmcnt(4)
	v_mfma_f32_32x32x16_bf16 v[64:79], v[186:189], v[128:131], v[64:79]
	v_exp_f32_e32 v81, v88
	v_exp_f32_e32 v82, v89
	v_add_f32_e32 v80, v81, v80
	v_cvt_pk_bf16_f32 v100, v81, v82
	v_add_f32_e32 v80, v82, v80
	s_waitcnt lgkmcnt(0)
	v_mfma_f32_32x32x16_bf16 v[48:63], v[190:193], v[112:115], v[48:63]
	v_exp_f32_e32 v81, v90
	v_exp_f32_e32 v82, v91
	v_add_f32_e32 v80, v81, v80
	v_cvt_pk_bf16_f32 v101, v81, v82
	v_add_f32_e32 v80, v82, v80
	v_mfma_f32_32x32x16_bf16 v[48:63], v[194:197], v[104:107], v[48:63]
	v_exp_f32_e32 v81, v92
	v_exp_f32_e32 v82, v93
	v_add_f32_e32 v80, v81, v80
	v_cvt_pk_bf16_f32 v102, v81, v82
	v_add_f32_e32 v80, v82, v80
	v_mfma_f32_32x32x16_bf16 v[32:47], v[198:201], v[112:115], v[32:47]
	v_exp_f32_e32 v81, v94
	v_exp_f32_e32 v82, v95
	v_add_f32_e32 v80, v81, v80
	v_cvt_pk_bf16_f32 v103, v81, v82
	v_add_f32_e32 v164, v82, v80
	v_exp_f32_e32 v64, v64
	v_exp_f32_e32 v65, v65
	s_nop 0
	v_add_f32_e32 v165, v65, v64
	v_cvt_pk_bf16_f32 v186, v64, v65
	v_mfma_f32_32x32x16_bf16 v[32:47], v[230:233], v[104:107], v[32:47]
	ds_read_b128 v[80:83], v168 offset:4608
	ds_read_b128 v[112:115], v168 offset:4640
	ds_read_b128 v[108:111], v168 offset:4672
	v_cmp_nge_f32_e64 s[8:9], s62, v164
	v_cmp_gt_f32_e32 vcc, s75, v164
	s_and_b64 s[6:7], s[6:7], vcc
	s_or_b64 s[6:7], s[6:7], s[8:9]
	ds_read_b128 v[104:107], v168 offset:4704
	s_waitcnt lgkmcnt(1)
; #define LAS __attribute__((address_space(3)))
; template <int MODE, bool FAST> __device__ __forceinline__ bool attn_unit(LAS unsigned char* lds, const AttU& U, const int wv) {
;     ...
;     pb[1][0] = (bf16x8){0, 0, 0, 0, 0, 0, 0, 0}; pb[1][1] = pb[1][0];
;     ATT_QK(0, 0, 0);
;     bf16x8 kpre[NPRE > 0 ? NPRE : 1];
; #pragma unroll
;     for (int i_ = 0; i_ < NPRE; ++i_) kpre[i_] = *(LAS const bf16x8*)(lds + koff + i_ * 32);
	v_mfma_f32_32x32x16_bf16 v[80:95], v[80:83], v[148:151], 0
	ds_read_b128 v[190:193], v168 offset:9216
	ds_read_b128 v[194:197], v168 offset:9248
	ds_read_b128 v[198:201], v168 offset:13824
	ds_read_b128 v[230:233], v168 offset:13856
	v_exp_f32_e32 v64, v66
	v_exp_f32_e32 v65, v67
	v_add_f32_e32 v66, v64, v165
	v_add_f32_e32 v66, v65, v66
	v_cvt_pk_bf16_f32 v187, v64, v65
	v_mfma_f32_32x32x16_bf16 v[80:95], v[112:115], v[152:155], v[80:95]
	v_exp_f32_e32 v64, v68
	v_exp_f32_e32 v65, v69
	v_add_f32_e32 v66, v64, v66
	v_cvt_pk_bf16_f32 v188, v64, v65
	v_add_f32_e32 v64, v65, v66
	v_mfma_f32_32x32x16_bf16 v[80:95], v[108:111], v[156:159], v[80:95]
	v_exp_f32_e32 v65, v70
	v_exp_f32_e32 v66, v71
	v_add_f32_e32 v64, v65, v64
	v_cvt_pk_bf16_f32 v189, v65, v66
	v_add_f32_e32 v64, v66, v64
	s_waitcnt lgkmcnt(4)
	v_mfma_f32_32x32x16_bf16 v[80:95], v[104:107], v[160:163], v[80:95]
	v_exp_f32_e32 v65, v72
	v_exp_f32_e32 v66, v73
	v_add_f32_e32 v64, v65, v64
	v_cvt_pk_bf16_f32 v108, v65, v66
	v_add_f32_e32 v64, v66, v64
	s_waitcnt lgkmcnt(0)
	v_mfma_f32_32x32x16_bf16 v[16:31], v[190:193], v[96:99], v[16:31]
	v_exp_f32_e32 v65, v74
	v_exp_f32_e32 v66, v75
	v_add_f32_e32 v64, v65, v64
	v_cvt_pk_bf16_f32 v109, v65, v66
	v_add_f32_e32 v64, v66, v64
	v_mfma_f32_32x32x16_bf16 v[16:31], v[194:197], v[100:103], v[16:31]
	v_exp_f32_e32 v65, v76
	v_exp_f32_e32 v66, v77
	v_add_f32_e32 v64, v65, v64
	v_cvt_pk_bf16_f32 v110, v65, v66
	v_add_f32_e32 v64, v66, v64
	v_mfma_f32_32x32x16_bf16 v[0:15], v[198:201], v[96:99], v[0:15]
	v_exp_f32_e32 v65, v78
	v_exp_f32_e32 v66, v79
	v_add_f32_e32 v64, v65, v64
	v_cvt_pk_bf16_f32 v111, v65, v66
	v_add_f32_e32 v104, v66, v64
	v_exp_f32_e32 v68, v80
	v_exp_f32_e32 v69, v81
	s_nop 0
	v_add_f32_e32 v81, v69, v68
	v_cvt_pk_bf16_f32 v80, v68, v69
	v_mfma_f32_32x32x16_bf16 v[0:15], v[230:233], v[100:103], v[0:15]
	ds_read_b128 v[64:67], v168 offset:18432
	ds_read_b128 v[96:99], v168 offset:18464
	ds_read_b128 v[112:115], v168 offset:18496
	v_cmp_nge_f32_e64 s[8:9], s62, v104
	ds_read_b128 v[100:103], v168 offset:18528
	s_waitcnt lgkmcnt(1)
	v_mfma_f32_32x32x16_bf16 v[64:79], v[64:67], v[116:119], 0
	ds_read_b128 v[190:193], v168 offset:9280
	ds_read_b128 v[194:197], v168 offset:9312
	ds_read_b128 v[198:201], v168 offset:13888
	ds_read_b128 v[230:233], v168 offset:13920
	v_exp_f32_e32 v82, v82
	v_exp_f32_e32 v83, v83
	v_add_f32_e32 v81, v82, v81
	v_add_f32_e32 v105, v83, v81
	v_cvt_pk_bf16_f32 v81, v82, v83
	v_mfma_f32_32x32x16_bf16 v[64:79], v[96:99], v[120:123], v[64:79]
	v_exp_f32_e32 v82, v84
	v_exp_f32_e32 v83, v85
	v_add_f32_e32 v84, v82, v105
	v_cvt_pk_bf16_f32 v82, v82, v83
	v_add_f32_e32 v83, v83, v84
	v_mfma_f32_32x32x16_bf16 v[64:79], v[112:115], v[124:127], v[64:79]
	v_exp_f32_e32 v84, v86
	v_exp_f32_e32 v85, v87
	v_add_f32_e32 v86, v84, v83
	v_cvt_pk_bf16_f32 v83, v84, v85
	v_add_f32_e32 v84, v85, v86
	s_waitcnt lgkmcnt(4)
	v_mfma_f32_32x32x16_bf16 v[64:79], v[100:103], v[128:131], v[64:79]
	v_exp_f32_e32 v85, v88
	v_exp_f32_e32 v86, v89
	v_add_f32_e32 v87, v85, v84
	v_cvt_pk_bf16_f32 v84, v85, v86
	v_add_f32_e32 v85, v86, v87
	s_waitcnt lgkmcnt(0)
	v_mfma_f32_32x32x16_bf16 v[48:63], v[190:193], v[186:189], v[48:63]
	v_exp_f32_e32 v86, v90
	v_exp_f32_e32 v87, v91
	v_add_f32_e32 v88, v86, v85
	v_cvt_pk_bf16_f32 v85, v86, v87
	v_add_f32_e32 v86, v87, v88
	v_mfma_f32_32x32x16_bf16 v[48:63], v[194:197], v[108:111], v[48:63]
	v_exp_f32_e32 v87, v92
	v_exp_f32_e32 v88, v93
	v_add_f32_e32 v89, v87, v86
	v_cvt_pk_bf16_f32 v86, v87, v88
	v_add_f32_e32 v87, v88, v89
	v_mfma_f32_32x32x16_bf16 v[32:47], v[198:201], v[186:189], v[32:47]
	v_exp_f32_e32 v88, v94
	v_exp_f32_e32 v89, v95
	v_add_f32_e32 v90, v88, v87
	v_cvt_pk_bf16_f32 v87, v88, v89
	v_add_f32_e32 v105, v89, v90
	v_mfma_f32_32x32x16_bf16 v[32:47], v[230:233], v[108:111], v[32:47]
	ds_read_b128 v[96:99], v168 offset:18432
	ds_read_b128 v[92:95], v168 offset:18464
	ds_read_b128 v[88:91], v168 offset:18496
	v_cmp_nge_f32_e64 s[10:11], s62, v105
	s_waitcnt lgkmcnt(0)
	s_barrier
	s_cmpk_gt_u32 s33, 0xfc
	s_cbranch_scc1 .LBB0_447
	v_add_u32_e32 v100, s49, v173
	s_waitcnt vmcnt(1)
	ds_write_b128 v100, v[140:143]
	s_waitcnt vmcnt(0)
	ds_write_b128 v100, v[144:147] offset:9216

.LBB0_927:
	s_add_i32 s6, s61, -1
	s_and_b32 s77, s61, 2
	s_and_b32 s79, s6, 3
	s_cmp_eq_u32 s61, 0
	s_cselect_b64 s[8:9], -1, 0
	s_mulk_i32 s79, 0x5800
	s_and_b64 s[6:7], s[8:9], exec
	s_mul_i32 s78, s77, 0x5800
	s_cselect_b32 s6, 0, s79
	s_add_i32 s76, s78, 0
	v_add_u32_e32 v199, s76, v241
	v_add_u32_e32 v210, s6, v244
	v_exp_f32_e32 v64, v64
	v_exp_f32_e32 v65, v65
	s_nop 0
	v_add_f32_e32 v84, v65, v64
	v_cvt_pk_bf16_f32 v178, v64, v65
	v_exp_f32_e32 v64, v66
	ds_read_b128 v[182:185], v199 offset:96
	ds_read_b128 v[246:249], v199 offset:128
	ds_read_b128 v[250:253], v199 offset:160
	v_exp_f32_e32 v65, v67
	v_add_f32_e32 v66, v64, v84
	v_mfma_f32_32x32x16_bf16 v[80:95], v[80:83], v[122:125], 0
	v_add_f32_e32 v66, v65, v66
	v_cvt_pk_bf16_f32 v179, v64, v65
	v_mfma_f32_32x32x16_bf16 v[80:95], v[174:177], v[126:129], v[80:95]
	v_exp_f32_e32 v64, v68
	v_exp_f32_e32 v65, v69
	v_add_f32_e32 v66, v64, v66
	v_add_f32_e32 v66, v65, v66
	v_cvt_pk_bf16_f32 v180, v64, v65
	v_mfma_f32_32x32x16_bf16 v[80:95], v[170:173], v[130:133], v[80:95]
	v_exp_f32_e32 v64, v70
	v_exp_f32_e32 v65, v71
	v_add_f32_e32 v66, v64, v66
	v_add_f32_e32 v170, v65, v66
	v_cvt_pk_bf16_f32 v181, v64, v65
	s_waitcnt lgkmcnt(0)
	v_mfma_f32_32x32x16_bf16 v[80:95], v[182:185], v[134:137], v[80:95]
	ds_read_b128 v[64:67], v210 offset:13376
	ds_read_b128 v[68:71], v210 offset:13408
	ds_read_b128 v[174:177], v210 offset:17984
	ds_read_b128 v[218:221], v210 offset:18016
	v_exp_f32_e32 v72, v72
	v_exp_f32_e32 v73, v73
	v_add_f32_e32 v170, v72, v170
	v_add_f32_e32 v171, v73, v170
	v_cvt_pk_bf16_f32 v170, v72, v73
	v_mfma_f32_32x32x16_bf16 v[80:95], v[246:249], v[154:157], v[80:95]
	v_exp_f32_e32 v72, v74
	v_exp_f32_e32 v73, v75
	v_add_f32_e32 v74, v72, v171
	v_add_f32_e32 v74, v73, v74
	v_cvt_pk_bf16_f32 v171, v72, v73
	v_mfma_f32_32x32x16_bf16 v[80:95], v[250:253], v[158:161], v[80:95]
	v_exp_f32_e32 v72, v76
	v_exp_f32_e32 v73, v77
	v_add_f32_e32 v74, v72, v74
	v_add_f32_e32 v74, v73, v74
	v_cvt_pk_bf16_f32 v172, v72, v73
	s_waitcnt lgkmcnt(0)
	v_mfma_f32_32x32x16_bf16 v[16:31], v[64:67], v[162:165], v[16:31]
	v_exp_f32_e32 v64, v78
	v_exp_f32_e32 v65, v79
	v_add_f32_e32 v66, v64, v74
	v_add_f32_e32 v246, v65, v66
	v_cvt_pk_bf16_f32 v173, v64, v65
	v_mfma_f32_32x32x16_bf16 v[0:15], v[174:177], v[162:165], v[0:15]
	ds_read_b128 v[64:67], v199 offset:6656
	ds_read_b128 v[182:185], v199 offset:6688
	ds_read_b128 v[174:177], v199 offset:6720
	v_cmp_nge_f32_e64 s[6:7], s48, v246
	v_cmp_gt_f32_e32 vcc, s49, v246
	v_mfma_f32_32x32x16_bf16 v[16:31], v[68:71], v[166:169], v[16:31]
	v_exp_f32_e32 v68, v80
	v_exp_f32_e32 v69, v81
	s_nop 0
	v_add_f32_e32 v70, v69, v68
	v_cvt_pk_bf16_f32 v162, v68, v69
	v_exp_f32_e32 v80, v82
	v_exp_f32_e32 v81, v83
	v_add_f32_e32 v82, v80, v70
	v_mfma_f32_32x32x16_bf16 v[0:15], v[218:221], v[166:169], v[0:15]
	s_and_b64 vcc, s[8:9], vcc
	s_or_b64 s[6:7], s[6:7], vcc
	v_add_u32_e32 v211, s76, v243
	ds_read_b128 v[166:169], v199 offset:6752
	ds_read_b128 v[218:221], v199 offset:6784
	ds_read_b128 v[248:251], v199 offset:6816
	s_waitcnt lgkmcnt(3)
	v_mfma_f32_32x32x16_bf16 v[64:79], v[64:67], v[98:101], 0
	v_add_f32_e32 v82, v81, v82
	v_cvt_pk_bf16_f32 v163, v80, v81
	v_mfma_f32_32x32x16_bf16 v[64:79], v[182:185], v[102:105], v[64:79]
	v_exp_f32_e32 v80, v84
	v_exp_f32_e32 v81, v85
	v_add_f32_e32 v82, v80, v82
	v_add_f32_e32 v82, v81, v82
	v_cvt_pk_bf16_f32 v164, v80, v81
	v_mfma_f32_32x32x16_bf16 v[64:79], v[174:177], v[106:109], v[64:79]
	v_exp_f32_e32 v80, v86
	v_exp_f32_e32 v81, v87
	v_add_f32_e32 v82, v80, v82
	v_add_f32_e32 v174, v81, v82
	v_cvt_pk_bf16_f32 v165, v80, v81
	s_waitcnt lgkmcnt(0)
	v_mfma_f32_32x32x16_bf16 v[64:79], v[166:169], v[110:113], v[64:79]
	ds_read_b128 v[80:83], v211 offset:13312
	ds_read_b128 v[84:87], v211 offset:13344
	ds_read_b128 v[182:185], v211 offset:17920
	ds_read_b128 v[222:225], v211 offset:17952
	v_exp_f32_e32 v88, v88
	v_exp_f32_e32 v89, v89
	v_add_f32_e32 v166, v88, v174
	v_add_f32_e32 v166, v89, v166
	v_cvt_pk_bf16_f32 v174, v88, v89
	v_mfma_f32_32x32x16_bf16 v[64:79], v[218:221], v[114:117], v[64:79]
	v_exp_f32_e32 v88, v90
	v_exp_f32_e32 v89, v91
	v_add_f32_e32 v90, v88, v166
	v_add_f32_e32 v90, v89, v90
	v_cvt_pk_bf16_f32 v175, v88, v89
	v_mfma_f32_32x32x16_bf16 v[64:79], v[248:251], v[118:121], v[64:79]
	v_exp_f32_e32 v88, v92
	v_exp_f32_e32 v89, v93
	v_add_f32_e32 v90, v88, v90
	v_add_f32_e32 v90, v89, v90
	v_cvt_pk_bf16_f32 v176, v88, v89
	s_waitcnt lgkmcnt(0)
	v_mfma_f32_32x32x16_bf16 v[48:63], v[80:83], v[178:181], v[48:63]
	v_exp_f32_e32 v80, v94
	v_exp_f32_e32 v81, v95
	v_add_f32_e32 v82, v80, v90
	v_add_f32_e32 v247, v81, v82
	v_cvt_pk_bf16_f32 v177, v80, v81
	v_mfma_f32_32x32x16_bf16 v[32:47], v[182:185], v[178:181], v[32:47]
	ds_read_b128 v[80:83], v199 offset:6656
	ds_read_b128 v[182:185], v199 offset:6688
	ds_read_b128 v[178:181], v199 offset:6720
	v_cmp_nge_f32_e64 s[10:11], s48, v247
	v_cmp_gt_f32_e32 vcc, s49, v247
	v_mfma_f32_32x32x16_bf16 v[48:63], v[84:87], v[170:173], v[48:63]
	v_exp_f32_e32 v64, v64
	v_exp_f32_e32 v65, v65
	s_nop 0
	v_add_f32_e32 v84, v65, v64
	v_cvt_pk_bf16_f32 v166, v64, v65
	v_exp_f32_e32 v64, v66
	v_exp_f32_e32 v65, v67
	v_add_f32_e32 v66, v64, v84
	v_mfma_f32_32x32x16_bf16 v[32:47], v[222:225], v[170:173], v[32:47]
	s_and_b64 s[8:9], s[8:9], vcc
	s_or_b64 s[8:9], s[8:9], s[10:11]
	ds_read_b128 v[170:173], v199 offset:6752
	ds_read_b128 v[218:221], v199 offset:6784
	ds_read_b128 v[222:225], v199 offset:6816
	s_waitcnt lgkmcnt(3)
; #define LAS __attribute__((address_space(3)))
; template <int MODE, bool FAST> __device__ __forceinline__ bool attn_unit(LAS unsigned char* lds, const AttU& U, const int wv) {
;     ...
;     pb[1][0] = (bf16x8){0, 0, 0, 0, 0, 0, 0, 0}; pb[1][1] = pb[1][0];
;     ATT_QK(0, 0, 0);
;     bf16x8 kpre[NPRE > 0 ? NPRE : 1];
; #pragma unroll
;     for (int i_ = 0; i_ < NPRE; ++i_) kpre[i_] = *(LAS const bf16x8*)(lds + koff + i_ * 32);
	v_mfma_f32_32x32x16_bf16 v[80:95], v[80:83], v[122:125], 0
	v_add_f32_e32 v66, v65, v66
	v_cvt_pk_bf16_f32 v167, v64, v65
	v_mfma_f32_32x32x16_bf16 v[80:95], v[182:185], v[126:129], v[80:95]
	v_exp_f32_e32 v64, v68
	v_exp_f32_e32 v65, v69
	v_add_f32_e32 v66, v64, v66
	v_add_f32_e32 v66, v65, v66
	v_cvt_pk_bf16_f32 v168, v64, v65
	v_mfma_f32_32x32x16_bf16 v[80:95], v[178:181], v[130:133], v[80:95]
	v_exp_f32_e32 v64, v70
	v_exp_f32_e32 v65, v71
	v_add_f32_e32 v66, v64, v66
	v_add_f32_e32 v178, v65, v66
	v_cvt_pk_bf16_f32 v169, v64, v65
	s_waitcnt lgkmcnt(0)
	v_mfma_f32_32x32x16_bf16 v[80:95], v[170:173], v[134:137], v[80:95]
	ds_read_b128 v[64:67], v211 offset:13312
	ds_read_b128 v[68:71], v211 offset:13344
	ds_read_b128 v[182:185], v211 offset:17920
	ds_read_b128 v[248:251], v211 offset:17952
	v_exp_f32_e32 v72, v72
	v_exp_f32_e32 v73, v73
	v_add_f32_e32 v170, v72, v178
	v_add_f32_e32 v170, v73, v170
	v_cvt_pk_bf16_f32 v178, v72, v73
	v_mfma_f32_32x32x16_bf16 v[80:95], v[218:221], v[154:157], v[80:95]
	v_exp_f32_e32 v72, v74
	v_exp_f32_e32 v73, v75
	v_add_f32_e32 v74, v72, v170
	v_add_f32_e32 v74, v73, v74
	v_cvt_pk_bf16_f32 v179, v72, v73
	v_mfma_f32_32x32x16_bf16 v[80:95], v[222:225], v[158:161], v[80:95]
	v_exp_f32_e32 v72, v76
	v_exp_f32_e32 v73, v77
	v_add_f32_e32 v74, v72, v74
	v_add_f32_e32 v74, v73, v74
	v_cvt_pk_bf16_f32 v180, v72, v73
	s_waitcnt lgkmcnt(0)
	v_mfma_f32_32x32x16_bf16 v[16:31], v[64:67], v[162:165], v[16:31]
	v_exp_f32_e32 v64, v78
	v_exp_f32_e32 v65, v79
	v_add_f32_e32 v66, v64, v74
	v_add_f32_e32 v210, v65, v66
	v_cvt_pk_bf16_f32 v181, v64, v65
	v_mfma_f32_32x32x16_bf16 v[0:15], v[182:185], v[162:165], v[0:15]
	v_add_u32_e32 v226, s78, v242
	ds_read_b128 v[64:67], v226 offset:22528
	ds_read_b128 v[170:173], v226 offset:22560
	ds_read_b128 v[182:185], v226 offset:22592
	v_cmp_nge_f32_e64 s[10:11], s48, v210
	v_mfma_f32_32x32x16_bf16 v[16:31], v[68:71], v[174:177], v[16:31]
	v_exp_f32_e32 v68, v80
	v_exp_f32_e32 v69, v81
	s_nop 0
	v_add_f32_e32 v70, v69, v68
	v_cvt_pk_bf16_f32 v162, v68, v69
	v_exp_f32_e32 v80, v82
	v_exp_f32_e32 v81, v83
	v_add_f32_e32 v82, v80, v70
	v_mfma_f32_32x32x16_bf16 v[0:15], v[248:251], v[174:177], v[0:15]
	ds_read_b128 v[174:177], v226 offset:22624
	ds_read_b128 v[218:221], v226 offset:22656
	ds_read_b128 v[222:225], v226 offset:22688
	s_waitcnt lgkmcnt(3)
	v_mfma_f32_32x32x16_bf16 v[64:79], v[64:67], v[98:101], 0
	v_add_f32_e32 v82, v81, v82
	v_cvt_pk_bf16_f32 v163, v80, v81
	v_mfma_f32_32x32x16_bf16 v[64:79], v[170:173], v[102:105], v[64:79]
	v_exp_f32_e32 v80, v84
	v_exp_f32_e32 v81, v85
	v_add_f32_e32 v82, v80, v82
	v_add_f32_e32 v82, v81, v82
	v_cvt_pk_bf16_f32 v164, v80, v81
	v_mfma_f32_32x32x16_bf16 v[64:79], v[182:185], v[106:109], v[64:79]
	v_exp_f32_e32 v80, v86
	v_exp_f32_e32 v81, v87
	v_add_f32_e32 v82, v80, v82
	v_add_f32_e32 v170, v81, v82
	v_cvt_pk_bf16_f32 v165, v80, v81
	s_waitcnt lgkmcnt(0)
	v_mfma_f32_32x32x16_bf16 v[64:79], v[174:177], v[110:113], v[64:79]
	ds_read_b128 v[80:83], v211 offset:13376
	ds_read_b128 v[84:87], v211 offset:13408
	ds_read_b128 v[182:185], v211 offset:17984
	ds_read_b128 v[248:251], v211 offset:18016
	v_exp_f32_e32 v88, v88
	v_exp_f32_e32 v89, v89
	v_add_f32_e32 v170, v88, v170
	v_add_f32_e32 v171, v89, v170
	v_cvt_pk_bf16_f32 v170, v88, v89
	v_mfma_f32_32x32x16_bf16 v[64:79], v[218:221], v[114:117], v[64:79]
	v_exp_f32_e32 v88, v90
	v_exp_f32_e32 v89, v91
	v_add_f32_e32 v90, v88, v171
	v_add_f32_e32 v90, v89, v90
	v_cvt_pk_bf16_f32 v171, v88, v89
	v_mfma_f32_32x32x16_bf16 v[64:79], v[222:225], v[118:121], v[64:79]
	v_exp_f32_e32 v88, v92
	v_exp_f32_e32 v89, v93
	v_add_f32_e32 v90, v88, v90
	v_add_f32_e32 v90, v89, v90
	v_cvt_pk_bf16_f32 v172, v88, v89
	s_waitcnt lgkmcnt(0)
	v_mfma_f32_32x32x16_bf16 v[48:63], v[80:83], v[166:169], v[48:63]
	v_exp_f32_e32 v80, v94
	v_exp_f32_e32 v81, v95
	v_add_f32_e32 v82, v80, v90
	v_add_f32_e32 v211, v81, v82
	v_cvt_pk_bf16_f32 v173, v80, v81
	v_mfma_f32_32x32x16_bf16 v[32:47], v[182:185], v[166:169], v[32:47]
	ds_read_b128 v[80:83], v226 offset:22528
	ds_read_b128 v[182:185], v226 offset:22560
	ds_read_b128 v[174:177], v226 offset:22592
	v_cmp_nge_f32_e64 s[12:13], s48, v211
	v_mfma_f32_32x32x16_bf16 v[48:63], v[84:87], v[178:181], v[48:63]
	s_waitcnt lgkmcnt(0)
	s_barrier
	v_mfma_f32_32x32x16_bf16 v[32:47], v[248:251], v[178:181], v[32:47]
	s_cmpk_gt_u32 s61, 0xfc
	s_cbranch_scc1 .LBB0_933
	s_add_i32 s24, s79, 0
	v_add_u32_e32 v84, s24, v238
	v_add_u32_e32 v85, s24, v245
	v_add_u32_e32 v86, s24, v198
	s_waitcnt vmcnt(1)
	ds_write_b128 v84, v[150:153]
	s_waitcnt vmcnt(0)
	ds_write_b64 v85, v[190:191] offset:128
	ds_write_b128 v86, v[138:141] offset:13312
